# v1 plus padding: P8 K-loop head moved to 28 mod 64, P9/P10 placement as v1
# speedup vs baseline: 1.0097x; 1.0060x over previous
;     __host__ __device__ bool next(int i, Unit& u) const {
;         const long L = (long)i * G + c; if (L >= nwg) return false;
;         int wgid = (int)L; { const int q = nwg / NXCD, r = nwg % NXCD, xcd = wgid % NXCD, off = wgid / NXCD; wgid = (xcd < r ? xcd * (q + 1) : r * (q + 1) + (xcd - r) * q) + off; }
;         const int nig = WGM * nN, gid = wgid / nig, fm = gid * WGM, gsz = (nM - fm) < WGM ? (nM - fm) : WGM;
;         u.pm = fm + ((wgid % nig) % gsz); u.pn = (wgid % nig) / gsz; return true;
; __global__ void __launch_bounds__(NTHR, 2) fwd_megakernel(Args args_unused) {
;     ...
;     xcd_barrier(xbar);
;     {
;         PH_COMMON
;         pg8::Gemm g{WSP(WS_U), WSP(WS_WGU), M, NGU, 2048}; pg8::StaticOrder S; S.init(M, NGU, G, bx);
;         epi::SwiGlu E{ws + WS_ACT, ACT_PITCH, FFN_H8, ACT_S8};
;         pg8::gemm_phase<epi::SwiGlu, pg8::StaticOrder, true, true>(lds, g, S, E);
.LBB0_712:
	s_or_b64 exec, exec, s[6:7]
	s_mov_b64 s[6:7], s[28:29]
	s_waitcnt lgkmcnt(0)
	v_mov_b32_e32 v0, v230
	v_mov_b32_e32 v8, v230
	s_cmpk_lt_i32 s2, 0x1600
	s_barrier
	s_nop 0
	s_nop 0
	s_nop 0
	s_nop 0
	s_nop 0
	s_nop 0
	s_nop 0
	s_nop 0
	s_nop 0
	s_nop 0
	s_nop 0
	s_nop 0
	s_nop 0
	s_nop 0
	s_cselect_b64 s[10:11], -1, 0
	s_cmpk_gt_i32 s2, 0x15ff
	v_readfirstlane_b32 s1, v8
	s_cbranch_scc1 .LBB0_714
	s_ashr_i32 s3, s2, 31
	s_lshr_b32 s3, s3, 29
	s_add_i32 s3, s2, s3
	s_ashr_i32 s8, s3, 3
	s_and_b32 s3, s3, -8
	s_sub_i32 s3, s2, s3
	s_cmp_lt_i32 s3, 0
	s_movk_i32 s9, 0x2c1
	s_cselect_b32 s9, s9, 0x2c0
	s_mul_i32 s3, s3, s9
	s_add_i32 s3, s3, s8
	s_mul_hi_i32 s8, s3, 0x2e8ba2e9
	s_lshr_b32 s9, s8, 31
	s_ashr_i32 s8, s8, 6
	s_add_i32 s8, s8, s9
	s_lshl_b32 s9, s8, 3
	s_mulk_i32 s8, 0x160
	s_sub_i32 s3, s3, s8
	s_sext_i32_i16 s8, s3
	s_bfe_u32 s8, s8, 0x3001c
	s_add_i32 s8, s3, s8
	s_sext_i32_i16 s12, s8
	s_and_b32 s8, s8, 0xfff8
	s_sub_i32 s3, s3, s8
	s_sext_i32_i16 s3, s3
	s_add_i32 s26, s9, s3
	s_ashr_i32 s8, s12, 3

; __global__ void __launch_bounds__(NTHR, 2) fwd_megakernel(Args args_unused) {
;     ...
;     xcd_barrier(xbar);
;     {
;         PH_COMMON
;         pg8::Gemm g{WSP(WS_ACT), WSP(WS_WD), M, 2048, ACT_PITCH / 2, FFN_T8}; pg8::StaticOrder S; S.init(M, 2048, G, bx);
;         epi::PlainMix E{WSP(WS_F), 2048, FFN_T8, 1.f / (ACT_S8 * WD_S8)};
.LBB0_814:
	s_or_b64 exec, exec, s[6:7]
	s_mov_b64 s[6:7], s[28:29]
	s_waitcnt lgkmcnt(0)
	v_mov_b32_e32 v0, v230
	v_mov_b32_e32 v8, v230
	s_barrier
	s_nop 0
	s_nop 0
	s_and_b64 vcc, exec, s[4:5]
	v_readfirstlane_b32 s1, v8
	s_cbranch_vccnz .LBB0_844
	s_ashr_i32 s3, s2, 31
	s_load_dwordx2 s[4:5], s[6:7], 0xe0
	s_lshr_b32 s6, s3, 29
	s_add_i32 s9, s2, s6
	s_and_b32 s6, s9, -8
	s_sub_i32 s10, s2, s6
	s_cmp_gt_i32 s10, -1
	s_cbranch_scc0 .LBB0_817
	s_lshl_b32 s8, s10, 7
	s_cbranch_execz .LBB0_818
	s_branch .LBB0_819
